# attention loop VALU trimmed: packed row-sum tree, packed score-minus-max, redundant max canonicalisations removed
# baseline (speedup 1.0000x reference)
.LBB0_1902:
	s_or_b64 exec, exec, s[2:3]
	s_and_b32 s2, 1, s8
	s_cselect_b32 s3, 0, 0x5800
	s_add_i32 s3, s3, 0
	v_add3_u32 v92, s3, v245, v210
	ds_read_b128 v[80:83], v92
	ds_read_b128 v[84:87], v92 offset:32
	ds_read_b128 v[88:91], v92 offset:6656
	ds_read_b128 v[188:191], v92 offset:6688
	s_waitcnt lgkmcnt(0)
	v_mfma_f32_32x32x16_bf16 v[112:127], v[80:83], v[176:179], 0
	v_mfma_f32_32x32x16_bf16 v[96:111], v[80:83], v[152:155], 0
	v_mfma_f32_32x32x16_bf16 v[112:127], v[84:87], v[172:175], v[112:127]
	v_mfma_f32_32x32x16_bf16 v[96:111], v[84:87], v[148:151], v[96:111]
	ds_read_b128 v[80:83], v92 offset:64
	ds_read_b128 v[84:87], v92 offset:96
	ds_read_b128 v[194:197], v92 offset:6720
	ds_read_b128 v[246:249], v92 offset:6752
	s_waitcnt lgkmcnt(0)
	v_mfma_f32_32x32x16_bf16 v[112:127], v[80:83], v[168:171], v[112:127]
	v_mfma_f32_32x32x16_bf16 v[96:111], v[80:83], v[144:147], v[96:111]
	v_mfma_f32_32x32x16_bf16 v[112:127], v[84:87], v[164:167], v[112:127]
	v_mfma_f32_32x32x16_bf16 v[96:111], v[84:87], v[140:143], v[96:111]
	ds_read_b128 v[80:83], v92 offset:128
	ds_read_b128 v[84:87], v92 offset:160
	ds_read_b128 v[200:203], v92 offset:6784
	ds_read_b128 v[224:227], v92 offset:6816
	s_waitcnt lgkmcnt(0)
	v_mfma_f32_32x32x16_bf16 v[112:127], v[80:83], v[160:163], v[112:127]
	v_mfma_f32_32x32x16_bf16 v[96:111], v[80:83], v[136:139], v[96:111]
	v_mfma_f32_32x32x16_bf16 v[64:79], v[88:91], v[176:179], 0
	v_mfma_f32_32x32x16_bf16 v[112:127], v[84:87], v[156:159], v[112:127]
	v_mfma_f32_32x32x16_bf16 v[96:111], v[84:87], v[132:135], v[96:111]
	s_nop 10
	v_mfma_f32_32x32x16_bf16 v[80:95], v[88:91], v[152:155], 0
	v_mfma_f32_32x32x16_bf16 v[64:79], v[188:191], v[172:175], v[64:79]
	v_mfma_f32_32x32x16_bf16 v[80:95], v[188:191], v[148:151], v[80:95]
	global_load_dwordx4 v[188:191], v[212:213], off
	v_mfma_f32_32x32x16_bf16 v[64:79], v[194:197], v[168:171], v[64:79]
	v_mfma_f32_32x32x16_bf16 v[64:79], v[246:249], v[164:167], v[64:79]
	v_mfma_f32_32x32x16_bf16 v[64:79], v[200:203], v[160:163], v[64:79]
	v_mfma_f32_32x32x16_bf16 v[80:95], v[194:197], v[144:147], v[80:95]
	v_mfma_f32_32x32x16_bf16 v[64:79], v[224:227], v[156:159], v[64:79]
	v_mfma_f32_32x32x16_bf16 v[80:95], v[246:249], v[140:143], v[80:95]
	s_nop 10
	v_max_f32_e32 v218, v112, v64
	v_max3_f32 v218, v218, v113, v65
	v_max3_f32 v218, v218, v114, v66
	v_max3_f32 v194, v218, v115, v67
	v_max3_f32 v194, v194, v116, v68
	v_max3_f32 v194, v194, v117, v69
	v_mfma_f32_32x32x16_bf16 v[80:95], v[200:203], v[136:139], v[80:95]
	v_max3_f32 v194, v194, v118, v70
	v_max3_f32 v194, v194, v119, v71
	v_max3_f32 v194, v194, v120, v72
	v_max3_f32 v194, v194, v121, v73
	v_max3_f32 v194, v194, v122, v74
	v_max3_f32 v194, v194, v123, v75
	v_max3_f32 v194, v194, v124, v76
	v_max3_f32 v194, v194, v125, v77
	v_mfma_f32_32x32x16_bf16 v[80:95], v[224:227], v[132:135], v[80:95]
	v_max3_f32 v194, v194, v126, v78
	v_max3_f32 v194, v194, v127, v79
	v_mov_b32_e32 v195, v194
	s_nop 1
	v_permlane32_swap_b32_e32 v194, v195
	v_max_f32_e32 v246, v194, v195
	v_add_f32_e32 v194, 0x41000000, v239
	v_cmp_gt_f32_e32 vcc, v246, v194
	s_cbranch_vccz .LBB0_1904
	v_max_f32_e32 v194, v246, v246
	v_max_f32_e32 v195, v239, v239
	v_max_f32_e32 v195, v195, v194
	v_sub_f32_e32 v194, v239, v195
	v_exp_f32_e32 v194, v194
	v_mov_b32_e32 v239, v195
	v_pk_mul_f32 v[46:47], v[46:47], v[194:195] op_sel_hi:[1,0]
	v_pk_mul_f32 v[44:45], v[44:45], v[194:195] op_sel_hi:[1,0]
	v_pk_mul_f32 v[42:43], v[42:43], v[194:195] op_sel_hi:[1,0]
	v_pk_mul_f32 v[40:41], v[40:41], v[194:195] op_sel_hi:[1,0]
	v_pk_mul_f32 v[38:39], v[38:39], v[194:195] op_sel_hi:[1,0]
	v_pk_mul_f32 v[36:37], v[36:37], v[194:195] op_sel_hi:[1,0]
	v_pk_mul_f32 v[34:35], v[34:35], v[194:195] op_sel_hi:[1,0]
	v_pk_mul_f32 v[32:33], v[32:33], v[194:195] op_sel_hi:[1,0]
	v_pk_mul_f32 v[62:63], v[62:63], v[194:195] op_sel_hi:[1,0]
	v_pk_mul_f32 v[60:61], v[60:61], v[194:195] op_sel_hi:[1,0]
	v_pk_mul_f32 v[58:59], v[58:59], v[194:195] op_sel_hi:[1,0]
	v_pk_mul_f32 v[56:57], v[56:57], v[194:195] op_sel_hi:[1,0]
	v_pk_mul_f32 v[54:55], v[54:55], v[194:195] op_sel_hi:[1,0]
	v_pk_mul_f32 v[52:53], v[52:53], v[194:195] op_sel_hi:[1,0]
	v_pk_mul_f32 v[50:51], v[50:51], v[194:195] op_sel_hi:[1,0]
	v_pk_mul_f32 v[48:49], v[48:49], v[194:195] op_sel_hi:[1,0]
	v_mul_f32_e32 v193, v193, v194
.LBB0_1904:
	v_max_f32_e32 v194, v96, v80
	v_max3_f32 v194, v194, v97, v81
	v_max3_f32 v194, v194, v98, v82
	v_max3_f32 v194, v194, v99, v83
	v_max3_f32 v194, v194, v100, v84
	v_max3_f32 v194, v194, v101, v85
	v_max3_f32 v194, v194, v102, v86
	v_max3_f32 v194, v194, v103, v87
	v_max3_f32 v194, v194, v104, v88
	v_max3_f32 v194, v194, v105, v89
	v_max3_f32 v194, v194, v106, v90
	v_max3_f32 v194, v194, v107, v91
	v_max3_f32 v194, v194, v108, v92
	v_max3_f32 v194, v194, v109, v93
	v_max3_f32 v194, v194, v110, v94
	v_max3_f32 v194, v194, v111, v95
	v_mov_b32_e32 v195, v194
	s_nop 1
	v_permlane32_swap_b32_e32 v194, v195
	v_max_f32_e32 v246, v194, v195
	v_add_f32_e32 v194, 0x41000000, v238
	v_cmp_gt_f32_e32 vcc, v246, v194
	s_cbranch_vccz .LBB0_1906
	v_max_f32_e32 v194, v246, v246
	v_max_f32_e32 v195, v238, v238
	v_max_f32_e32 v195, v195, v194
	v_sub_f32_e32 v194, v238, v195
	v_exp_f32_e32 v194, v194
	v_mov_b32_e32 v238, v195
	v_pk_mul_f32 v[30:31], v[30:31], v[194:195] op_sel_hi:[1,0]
	v_pk_mul_f32 v[28:29], v[28:29], v[194:195] op_sel_hi:[1,0]
	v_pk_mul_f32 v[26:27], v[26:27], v[194:195] op_sel_hi:[1,0]
	v_pk_mul_f32 v[24:25], v[24:25], v[194:195] op_sel_hi:[1,0]
	v_pk_mul_f32 v[22:23], v[22:23], v[194:195] op_sel_hi:[1,0]
	v_pk_mul_f32 v[20:21], v[20:21], v[194:195] op_sel_hi:[1,0]
	v_pk_mul_f32 v[18:19], v[18:19], v[194:195] op_sel_hi:[1,0]
	v_pk_mul_f32 v[16:17], v[16:17], v[194:195] op_sel_hi:[1,0]
	v_pk_mul_f32 v[14:15], v[14:15], v[194:195] op_sel_hi:[1,0]
	v_pk_mul_f32 v[12:13], v[12:13], v[194:195] op_sel_hi:[1,0]
	v_pk_mul_f32 v[10:11], v[10:11], v[194:195] op_sel_hi:[1,0]
	v_pk_mul_f32 v[8:9], v[8:9], v[194:195] op_sel_hi:[1,0]
	v_pk_mul_f32 v[6:7], v[6:7], v[194:195] op_sel_hi:[1,0]
	v_pk_mul_f32 v[4:5], v[4:5], v[194:195] op_sel_hi:[1,0]
	v_pk_mul_f32 v[2:3], v[2:3], v[194:195] op_sel_hi:[1,0]
	v_pk_mul_f32 v[0:1], v[0:1], v[194:195] op_sel_hi:[1,0]
	v_mul_f32_e32 v131, v131, v194
.LBB0_1906:
	v_mul_u32_u24_e32 v200, 0x90, v211
	v_add3_u32 v218, s3, v200, v130
	v_add_u32_e32 v247, 0x3000, v218
	v_add_u32_e32 v248, 0x4000, v218
	ds_read2_b64 v[200:203], v247 offset0:128 offset1:130
	ds_read2_b64 v[224:227], v248 offset0:192 offset1:194
	v_sub_f32_e32 v99, v99, v238
	v_exp_f32_e32 v246, v99
	v_pk_add_f32 v[100:101], v[100:101], v[238:239] op_sel_hi:[1,0] neg_lo:[0,1] neg_hi:[0,1]
	v_exp_f32_e32 v100, v100
	v_pk_add_f32 v[112:113], v[112:113], v[238:239] op_sel:[0,1] op_sel_hi:[1,1] neg_lo:[0,1] neg_hi:[0,1]
	v_pk_add_f32 v[114:115], v[114:115], v[238:239] op_sel:[0,1] op_sel_hi:[1,1] neg_lo:[0,1] neg_hi:[0,1]
	v_pk_add_f32 v[116:117], v[116:117], v[238:239] op_sel:[0,1] op_sel_hi:[1,1] neg_lo:[0,1] neg_hi:[0,1]
	v_pk_add_f32 v[118:119], v[118:119], v[238:239] op_sel:[0,1] op_sel_hi:[1,1] neg_lo:[0,1] neg_hi:[0,1]
	v_exp_f32_e32 v101, v101
	v_sub_f32_e32 v102, v102, v238
	v_exp_f32_e32 v112, v112
	v_exp_f32_e32 v113, v113
	v_exp_f32_e32 v114, v114
	v_exp_f32_e32 v115, v115
	v_exp_f32_e32 v116, v116
	v_exp_f32_e32 v117, v117
	v_exp_f32_e32 v118, v118
	v_exp_f32_e32 v119, v119
	v_pk_add_f32 v[96:97], v[96:97], v[238:239] op_sel_hi:[1,0] neg_lo:[0,1] neg_hi:[0,1]
	v_sub_f32_e32 v98, v98, v238
	v_exp_f32_e32 v102, v102
	v_sub_f32_e32 v103, v103, v238
	v_exp_f32_e32 v96, v96
	v_exp_f32_e32 v97, v97
	v_exp_f32_e32 v98, v98
	v_exp_f32_e32 v103, v103
	v_cvt_pk_bf16_f32 v194, v112, v113
	v_cvt_pk_bf16_f32 v195, v114, v115
	v_cvt_pk_bf16_f32 v196, v116, v117
	v_cvt_pk_bf16_f32 v197, v118, v119
	ds_read2_b64 v[218:221], v247 offset0:132 offset1:134
	v_pk_add_f32 v[120:121], v[120:121], v[238:239] op_sel:[0,1] op_sel_hi:[1,1] neg_lo:[0,1] neg_hi:[0,1]
	s_waitcnt lgkmcnt(0)
	v_mfma_f32_32x32x16_bf16 v[32:47], v[200:203], v[194:197], v[32:47]
	v_pk_add_f32 v[122:123], v[122:123], v[238:239] op_sel:[0,1] op_sel_hi:[1,1] neg_lo:[0,1] neg_hi:[0,1]
	v_pk_add_f32 v[124:125], v[124:125], v[238:239] op_sel:[0,1] op_sel_hi:[1,1] neg_lo:[0,1] neg_hi:[0,1]
	v_sub_f32_e32 v126, v126, v239
	v_sub_f32_e32 v99, v127, v239
	v_mfma_f32_32x32x16_bf16 v[48:63], v[224:227], v[194:197], v[48:63]
	v_cvt_pk_bf16_f32 v194, v96, v97
	v_cvt_pk_bf16_f32 v195, v98, v246
	v_cvt_pk_bf16_f32 v196, v100, v101
	v_cvt_pk_bf16_f32 v197, v102, v103
	v_exp_f32_e32 v120, v120
	v_exp_f32_e32 v121, v121
	v_exp_f32_e32 v122, v122
	v_mfma_f32_32x32x16_bf16 v[16:31], v[200:203], v[194:197], v[16:31]
	v_exp_f32_e32 v123, v123
	v_exp_f32_e32 v124, v124
	v_exp_f32_e32 v125, v125
	v_exp_f32_e32 v126, v126
	v_exp_f32_e32 v99, v99
	v_pk_add_f32 v[104:105], v[104:105], v[238:239] op_sel_hi:[1,0] neg_lo:[0,1] neg_hi:[0,1]
	v_mfma_f32_32x32x16_bf16 v[0:15], v[224:227], v[194:197], v[0:15]
	ds_read2_b64 v[194:197], v248 offset0:196 offset1:198
	v_pk_add_f32 v[106:107], v[106:107], v[238:239] op_sel_hi:[1,0] neg_lo:[0,1] neg_hi:[0,1]
	v_pk_add_f32 v[108:109], v[108:109], v[238:239] op_sel_hi:[1,0] neg_lo:[0,1] neg_hi:[0,1]
	v_pk_add_f32 v[110:111], v[110:111], v[238:239] op_sel_hi:[1,0] neg_lo:[0,1] neg_hi:[0,1]
	v_exp_f32_e32 v104, v104
	v_exp_f32_e32 v105, v105
	v_exp_f32_e32 v106, v106
	v_exp_f32_e32 v107, v107
	v_exp_f32_e32 v108, v108
	v_exp_f32_e32 v109, v109
	v_exp_f32_e32 v110, v110
	v_exp_f32_e32 v111, v111
	v_cvt_pk_bf16_f32 v200, v120, v121
	v_cvt_pk_bf16_f32 v201, v122, v123
	v_cvt_pk_bf16_f32 v202, v124, v125
	v_cvt_pk_bf16_f32 v203, v126, v99
	ds_read2_b64 v[224:227], v247 offset0:136 offset1:138
	v_pk_add_f32 v[64:65], v[64:65], v[238:239] op_sel:[0,1] op_sel_hi:[1,1] neg_lo:[0,1] neg_hi:[0,1]
	v_mfma_f32_32x32x16_bf16 v[32:47], v[218:221], v[200:203], v[32:47]
	v_pk_add_f32 v[66:67], v[66:67], v[238:239] op_sel:[0,1] op_sel_hi:[1,1] neg_lo:[0,1] neg_hi:[0,1]
	v_pk_add_f32 v[68:69], v[68:69], v[238:239] op_sel:[0,1] op_sel_hi:[1,1] neg_lo:[0,1] neg_hi:[0,1]
	v_pk_add_f32 v[70:71], v[70:71], v[238:239] op_sel:[0,1] op_sel_hi:[1,1] neg_lo:[0,1] neg_hi:[0,1]
	s_waitcnt lgkmcnt(0)
	v_mfma_f32_32x32x16_bf16 v[48:63], v[194:197], v[200:203], v[48:63]
	v_cvt_pk_bf16_f32 v200, v104, v105
	v_cvt_pk_bf16_f32 v201, v106, v107
	v_cvt_pk_bf16_f32 v202, v108, v109
	v_cvt_pk_bf16_f32 v203, v110, v111
	v_pk_add_f32 v[80:81], v[80:81], v[238:239] op_sel_hi:[1,0] neg_lo:[0,1] neg_hi:[0,1]
	v_pk_add_f32 v[82:83], v[82:83], v[238:239] op_sel_hi:[1,0] neg_lo:[0,1] neg_hi:[0,1]
	v_mfma_f32_32x32x16_bf16 v[0:15], v[194:197], v[200:203], v[0:15]
	ds_read2_b64 v[194:197], v248 offset0:200 offset1:202
	v_pk_add_f32 v[84:85], v[84:85], v[238:239] op_sel_hi:[1,0] neg_lo:[0,1] neg_hi:[0,1]
	v_pk_add_f32 v[86:87], v[86:87], v[238:239] op_sel_hi:[1,0] neg_lo:[0,1] neg_hi:[0,1]
	v_exp_f32_e32 v64, v64
	v_mfma_f32_32x32x16_bf16 v[16:31], v[218:221], v[200:203], v[16:31]
	v_exp_f32_e32 v65, v65
	v_exp_f32_e32 v66, v66
	v_exp_f32_e32 v67, v67
	v_exp_f32_e32 v68, v68
	v_exp_f32_e32 v69, v69
	v_exp_f32_e32 v70, v70
	v_exp_f32_e32 v71, v71
	v_exp_f32_e32 v80, v80
	v_exp_f32_e32 v81, v81
	v_exp_f32_e32 v82, v82
	v_exp_f32_e32 v83, v83
	v_exp_f32_e32 v84, v84
	v_exp_f32_e32 v85, v85
	v_exp_f32_e32 v86, v86
	v_exp_f32_e32 v87, v87
	v_cvt_pk_bf16_f32 v218, v64, v65
	v_cvt_pk_bf16_f32 v219, v66, v67
	v_cvt_pk_bf16_f32 v220, v68, v69
	v_cvt_pk_bf16_f32 v221, v70, v71
	v_cvt_pk_bf16_f32 v200, v80, v81
	v_cvt_pk_bf16_f32 v201, v82, v83
	v_cvt_pk_bf16_f32 v202, v84, v85
	v_cvt_pk_bf16_f32 v203, v86, v87
	v_mfma_f32_32x32x16_bf16 v[32:47], v[224:227], v[218:221], v[32:47]
	v_pk_add_f32 v[72:73], v[72:73], v[238:239] op_sel:[0,1] op_sel_hi:[1,1] neg_lo:[0,1] neg_hi:[0,1]
	v_pk_add_f32 v[74:75], v[74:75], v[238:239] op_sel:[0,1] op_sel_hi:[1,1] neg_lo:[0,1] neg_hi:[0,1]
	v_pk_add_f32 v[76:77], v[76:77], v[238:239] op_sel:[0,1] op_sel_hi:[1,1] neg_lo:[0,1] neg_hi:[0,1]
	v_pk_add_f32 v[78:79], v[78:79], v[238:239] op_sel:[0,1] op_sel_hi:[1,1] neg_lo:[0,1] neg_hi:[0,1]
	s_waitcnt lgkmcnt(0)
	v_mfma_f32_32x32x16_bf16 v[48:63], v[194:197], v[218:221], v[48:63]
	v_pk_add_f32 v[88:89], v[88:89], v[238:239] op_sel_hi:[1,0] neg_lo:[0,1] neg_hi:[0,1]
	v_pk_add_f32 v[90:91], v[90:91], v[238:239] op_sel_hi:[1,0] neg_lo:[0,1] neg_hi:[0,1]
	v_pk_add_f32 v[92:93], v[92:93], v[238:239] op_sel_hi:[1,0] neg_lo:[0,1] neg_hi:[0,1]
	v_mfma_f32_32x32x16_bf16 v[16:31], v[224:227], v[200:203], v[16:31]
	ds_read2_b64 v[224:227], v247 offset0:140 offset1:142
	v_pk_add_f32 v[94:95], v[94:95], v[238:239] op_sel_hi:[1,0] neg_lo:[0,1] neg_hi:[0,1]
	v_exp_f32_e32 v72, v72
	v_exp_f32_e32 v73, v73
	v_exp_f32_e32 v74, v74
	v_exp_f32_e32 v75, v75
	v_mfma_f32_32x32x16_bf16 v[0:15], v[194:197], v[200:203], v[0:15]
	ds_read2_b64 v[194:197], v248 offset0:204 offset1:206
	v_exp_f32_e32 v76, v76
	v_exp_f32_e32 v77, v77
	v_exp_f32_e32 v78, v78
	v_exp_f32_e32 v79, v79
	v_exp_f32_e32 v88, v88
	v_exp_f32_e32 v89, v89
	v_exp_f32_e32 v90, v90
	v_exp_f32_e32 v91, v91
	v_exp_f32_e32 v92, v92
	v_exp_f32_e32 v93, v93
	v_exp_f32_e32 v94, v94
	v_exp_f32_e32 v95, v95
	v_cvt_pk_bf16_f32 v218, v72, v73
	v_cvt_pk_bf16_f32 v219, v74, v75
	v_cvt_pk_bf16_f32 v220, v76, v77
	v_cvt_pk_bf16_f32 v221, v78, v79
	v_cvt_pk_bf16_f32 v200, v88, v89
	v_cvt_pk_bf16_f32 v201, v90, v91
	v_cvt_pk_bf16_f32 v202, v92, v93
	v_cvt_pk_bf16_f32 v203, v94, v95
	s_waitcnt lgkmcnt(0)
	v_mfma_f32_32x32x16_bf16 v[32:47], v[224:227], v[218:221], v[32:47]
	s_cmp_eq_u32 s2, 1
	s_cselect_b32 s2, 0x5800, 0
	s_add_i32 s9, s2, 0
	v_add3_u32 v127, s9, v240, v241
	s_waitcnt vmcnt(0)
	ds_write_b128 v127, v[184:187]
	v_mfma_f32_32x32x16_bf16 v[48:63], v[194:197], v[218:221], v[48:63]
	v_mfma_f32_32x32x16_bf16 v[16:31], v[224:227], v[200:203], v[16:31]
	v_mfma_f32_32x32x16_bf16 v[0:15], v[194:197], v[200:203], v[0:15]
	s_and_saveexec_b64 s[2:3], s[42:43]
	s_cbranch_execz .LBB0_1899
	v_add3_u32 v127, s9, v243, v242
	ds_write_b128 v127, v[180:183]
	s_branch .LBB0_1899
